# v23: v22 + EpiScale epilogue row-statistic loads issued before the wave-half alignment barrier
# speedup vs baseline: 1.0049x; 1.0018x over previous
.LBB0_468:
	s_add_u32 s62, s60, 0xfffc0080
	s_addc_u32 s63, s61, -1
	s_add_i32 s72, 0, 0x10000
	s_cmp_eq_u32 s71, 12
	s_cselect_b32 s65, s45, s63
	s_cselect_b32 s64, s55, s62
	v_add_u32_e32 v150, s72, v153
	s_cselect_b32 s63, s53, s70
	s_cselect_b32 s62, s68, s69
	s_add_i32 s74, 0, 0x14000
	ds_read_b128 v[142:145], v150
	ds_read_b128 v[146:149], v150 offset:1024
	ds_read_b128 v[156:159], v150 offset:2048
	ds_read_b128 v[160:163], v150 offset:3072
	v_add_u32_e32 v150, s74, v153
	ds_read_b128 v[164:167], v150
	ds_read_b128 v[168:171], v150 offset:1024
	ds_read_b128 v[172:175], v150 offset:2048
	ds_read_b128 v[176:179], v150 offset:3072
	v_lshl_add_u64 v[150:151], s[60:61], 0, v[138:139]
	s_add_i32 m0, s22, 0xc000
	ds_read_b128 v[180:183], v155
	ds_read_b128 v[184:187], v155 offset:1024
	ds_read_b128 v[196:199], v155 offset:2048
	ds_read_b128 v[200:203], v155 offset:3072
	ds_read_b128 v[228:231], v155 offset:4096
	ds_read_b128 v[232:235], v155 offset:5120
	ds_read_b128 v[236:239], v155 offset:6144
	ds_read_b128 v[240:243], v155 offset:7168
	global_load_lds_dwordx4 v[150:151], off
	v_lshl_add_u64 v[150:151], s[60:61], 0, v[140:141]
	s_add_i32 m0, s22, 0xe000
	s_nop 0
	global_load_lds_dwordx4 v[150:151], off
	s_waitcnt vmcnt(8)
	s_waitcnt lgkmcnt(0)
	s_barrier
	s_setprio 1
	s_waitcnt lgkmcnt(0)
	v_mfma_f32_16x16x32_bf16 v[126:129], v[142:145], v[180:183], v[126:129]
	v_mfma_f32_16x16x32_bf16 v[122:125], v[156:159], v[180:183], v[122:125]
	v_mfma_f32_16x16x32_bf16 v[114:117], v[142:145], v[196:199], v[114:117]
	v_mfma_f32_16x16x32_bf16 v[106:109], v[156:159], v[196:199], v[106:109]
	v_mfma_f32_16x16x32_bf16 v[98:101], v[142:145], v[228:231], v[98:101]
	v_mfma_f32_16x16x32_bf16 v[90:93], v[156:159], v[228:231], v[90:93]
	v_mfma_f32_16x16x32_bf16 v[82:85], v[142:145], v[236:239], v[82:85]
	v_mfma_f32_16x16x32_bf16 v[74:77], v[156:159], v[236:239], v[74:77]
	v_mfma_f32_16x16x32_bf16 v[126:129], v[146:149], v[184:187], v[126:129]
	v_mfma_f32_16x16x32_bf16 v[122:125], v[160:163], v[184:187], v[122:125]
	v_mfma_f32_16x16x32_bf16 v[114:117], v[146:149], v[200:203], v[114:117]
	v_mfma_f32_16x16x32_bf16 v[106:109], v[160:163], v[200:203], v[106:109]
	v_mfma_f32_16x16x32_bf16 v[98:101], v[146:149], v[232:235], v[98:101]
	v_mfma_f32_16x16x32_bf16 v[90:93], v[160:163], v[232:235], v[90:93]
	v_mfma_f32_16x16x32_bf16 v[82:85], v[146:149], v[240:243], v[82:85]
	v_mfma_f32_16x16x32_bf16 v[74:77], v[160:163], v[240:243], v[74:77]
	s_setprio 0
	s_setprio 1
	v_mfma_f32_16x16x32_bf16 v[118:121], v[164:167], v[180:183], v[118:121]
	v_mfma_f32_16x16x32_bf16 v[110:113], v[172:175], v[180:183], v[110:113]
	v_mfma_f32_16x16x32_bf16 v[102:105], v[164:167], v[196:199], v[102:105]
	v_mfma_f32_16x16x32_bf16 v[94:97], v[172:175], v[196:199], v[94:97]
	v_mfma_f32_16x16x32_bf16 v[86:89], v[164:167], v[228:231], v[86:89]
	v_mfma_f32_16x16x32_bf16 v[78:81], v[172:175], v[228:231], v[78:81]
	v_mfma_f32_16x16x32_bf16 v[70:73], v[164:167], v[236:239], v[70:73]
	v_mfma_f32_16x16x32_bf16 v[66:69], v[172:175], v[236:239], v[66:69]
	v_mfma_f32_16x16x32_bf16 v[118:121], v[168:171], v[184:187], v[118:121]
	v_mfma_f32_16x16x32_bf16 v[110:113], v[176:179], v[184:187], v[110:113]
	v_mfma_f32_16x16x32_bf16 v[102:105], v[168:171], v[200:203], v[102:105]
	v_mfma_f32_16x16x32_bf16 v[94:97], v[176:179], v[200:203], v[94:97]
	v_mfma_f32_16x16x32_bf16 v[86:89], v[168:171], v[232:235], v[86:89]
	v_mfma_f32_16x16x32_bf16 v[78:81], v[176:179], v[232:235], v[78:81]
	v_mfma_f32_16x16x32_bf16 v[70:73], v[168:171], v[240:243], v[70:73]
	v_mfma_f32_16x16x32_bf16 v[66:69], v[176:179], v[240:243], v[66:69]
	s_setprio 0
	s_barrier
	s_add_i32 s72, s72, s10
	v_lshl_add_u64 v[150:151], s[62:63], 0, v[0:1]
	s_mov_b32 m0, s72
	ds_read_b128 v[180:183], v155 offset:16384
	ds_read_b128 v[184:187], v155 offset:17408
	ds_read_b128 v[196:199], v155 offset:18432
	ds_read_b128 v[200:203], v155 offset:19456
	ds_read_b128 v[228:231], v155 offset:20480
	ds_read_b128 v[232:235], v155 offset:21504
	ds_read_b128 v[236:239], v155 offset:22528
	ds_read_b128 v[240:243], v155 offset:23552
	global_load_lds_dwordx4 v[150:151], off
	s_add_i32 m0, s72, 0x2000
	s_add_u32 s72, s62, 0x40000
	v_lshl_add_u64 v[188:189], s[62:63], 0, v[130:131]
	s_addc_u32 s73, s63, 0
	s_add_i32 s74, s74, s10
	global_load_lds_dwordx4 v[188:189], off
	v_lshl_add_u64 v[190:191], s[72:73], 0, v[0:1]
	s_mov_b32 m0, s74
	v_lshl_add_u64 v[192:193], s[64:65], 0, v[132:133]
	global_load_lds_dwordx4 v[190:191], off
	v_lshl_add_u64 v[190:191], s[72:73], 0, v[130:131]
	s_add_i32 m0, s74, 0x2000
	s_nop 0
	global_load_lds_dwordx4 v[190:191], off
	v_lshl_add_u64 v[190:191], s[64:65], 0, v[134:135]
	s_mov_b32 m0, s22
	s_nop 0
	global_load_lds_dwordx4 v[190:191], off
	s_mov_b32 m0, s23
	s_nop 0
	global_load_lds_dwordx4 v[192:193], off
	s_waitcnt vmcnt(8)
	s_waitcnt lgkmcnt(0)
	s_barrier
	s_setprio 1
	s_waitcnt lgkmcnt(0)
	v_mfma_f32_16x16x32_bf16 v[62:65], v[142:145], v[180:183], v[62:65]
	v_mfma_f32_16x16x32_bf16 v[58:61], v[156:159], v[180:183], v[58:61]
	v_mfma_f32_16x16x32_bf16 v[50:53], v[142:145], v[196:199], v[50:53]
	v_mfma_f32_16x16x32_bf16 v[42:45], v[156:159], v[196:199], v[42:45]
	v_mfma_f32_16x16x32_bf16 v[34:37], v[142:145], v[228:231], v[34:37]
	v_mfma_f32_16x16x32_bf16 v[26:29], v[156:159], v[228:231], v[26:29]
	v_mfma_f32_16x16x32_bf16 v[18:21], v[142:145], v[236:239], v[18:21]
	v_mfma_f32_16x16x32_bf16 v[10:13], v[156:159], v[236:239], v[10:13]
	v_mfma_f32_16x16x32_bf16 v[62:65], v[146:149], v[184:187], v[62:65]
	v_mfma_f32_16x16x32_bf16 v[58:61], v[160:163], v[184:187], v[58:61]
	v_mfma_f32_16x16x32_bf16 v[50:53], v[146:149], v[200:203], v[50:53]
	v_mfma_f32_16x16x32_bf16 v[42:45], v[160:163], v[200:203], v[42:45]
	v_mfma_f32_16x16x32_bf16 v[34:37], v[146:149], v[232:235], v[34:37]
	v_mfma_f32_16x16x32_bf16 v[26:29], v[160:163], v[232:235], v[26:29]
	v_mfma_f32_16x16x32_bf16 v[18:21], v[146:149], v[240:243], v[18:21]
	v_mfma_f32_16x16x32_bf16 v[10:13], v[160:163], v[240:243], v[10:13]
	s_setprio 0
	s_setprio 1
	v_mfma_f32_16x16x32_bf16 v[54:57], v[164:167], v[180:183], v[54:57]
	v_mfma_f32_16x16x32_bf16 v[46:49], v[172:175], v[180:183], v[46:49]
	v_mfma_f32_16x16x32_bf16 v[38:41], v[164:167], v[196:199], v[38:41]
	v_mfma_f32_16x16x32_bf16 v[30:33], v[172:175], v[196:199], v[30:33]
	v_mfma_f32_16x16x32_bf16 v[22:25], v[164:167], v[228:231], v[22:25]
	v_mfma_f32_16x16x32_bf16 v[14:17], v[172:175], v[228:231], v[14:17]
	v_mfma_f32_16x16x32_bf16 v[6:9], v[164:167], v[236:239], v[6:9]
	v_mfma_f32_16x16x32_bf16 v[2:5], v[172:175], v[236:239], v[2:5]
	v_mfma_f32_16x16x32_bf16 v[54:57], v[168:171], v[184:187], v[54:57]
	v_mfma_f32_16x16x32_bf16 v[46:49], v[176:179], v[184:187], v[46:49]
	v_mfma_f32_16x16x32_bf16 v[38:41], v[168:171], v[200:203], v[38:41]
	v_mfma_f32_16x16x32_bf16 v[30:33], v[176:179], v[200:203], v[30:33]
	v_mfma_f32_16x16x32_bf16 v[22:25], v[168:171], v[232:235], v[22:25]
	v_mfma_f32_16x16x32_bf16 v[14:17], v[176:179], v[232:235], v[14:17]
	v_mfma_f32_16x16x32_bf16 v[6:9], v[168:171], v[240:243], v[6:9]
	v_mfma_f32_16x16x32_bf16 v[2:5], v[176:179], v[240:243], v[2:5]
	s_setprio 0
	s_barrier
	s_add_i32 s72, 0, 0x1c000
	v_add_u32_e32 v160, s19, v153
	v_add_u32_e32 v176, s72, v153
	ds_read_b128 v[142:145], v160
	ds_read_b128 v[146:149], v160 offset:1024
	ds_read_b128 v[156:159], v160 offset:2048
	ds_read_b128 v[160:163], v160 offset:3072
	ds_read_b128 v[164:167], v176
	ds_read_b128 v[168:171], v176 offset:1024
	ds_read_b128 v[172:175], v176 offset:2048
	ds_read_b128 v[176:179], v176 offset:3072
	s_add_u32 s64, s64, 0x40000
	s_addc_u32 s65, s65, 0
	s_mov_b32 m0, s26
	v_lshl_add_u64 v[204:205], s[64:65], 0, v[134:135]
	ds_read_b128 v[180:183], v155 offset:32768
	ds_read_b128 v[184:187], v155 offset:33792
	ds_read_b128 v[196:199], v155 offset:34816
	ds_read_b128 v[200:203], v155 offset:35840
	ds_read_b128 v[228:231], v155 offset:36864
	ds_read_b128 v[232:235], v155 offset:37888
	ds_read_b128 v[236:239], v155 offset:38912
	ds_read_b128 v[240:243], v155 offset:39936
	global_load_lds_dwordx4 v[204:205], off
	v_lshl_add_u64 v[204:205], s[64:65], 0, v[132:133]
	s_mov_b32 m0, s38
	s_nop 0
	global_load_lds_dwordx4 v[204:205], off
	s_waitcnt vmcnt(8)
	s_waitcnt lgkmcnt(0)
	s_barrier
	s_setprio 1
	s_waitcnt lgkmcnt(0)
	v_mfma_f32_16x16x32_bf16 v[126:129], v[142:145], v[180:183], v[126:129]
	v_mfma_f32_16x16x32_bf16 v[122:125], v[156:159], v[180:183], v[122:125]
	v_mfma_f32_16x16x32_bf16 v[114:117], v[142:145], v[196:199], v[114:117]
	v_mfma_f32_16x16x32_bf16 v[106:109], v[156:159], v[196:199], v[106:109]
	v_mfma_f32_16x16x32_bf16 v[98:101], v[142:145], v[228:231], v[98:101]
	v_mfma_f32_16x16x32_bf16 v[90:93], v[156:159], v[228:231], v[90:93]
	v_mfma_f32_16x16x32_bf16 v[82:85], v[142:145], v[236:239], v[82:85]
	v_mfma_f32_16x16x32_bf16 v[74:77], v[156:159], v[236:239], v[74:77]
	v_mfma_f32_16x16x32_bf16 v[126:129], v[146:149], v[184:187], v[126:129]
	v_mfma_f32_16x16x32_bf16 v[122:125], v[160:163], v[184:187], v[122:125]
	v_mfma_f32_16x16x32_bf16 v[114:117], v[146:149], v[200:203], v[114:117]
	v_mfma_f32_16x16x32_bf16 v[106:109], v[160:163], v[200:203], v[106:109]
	v_mfma_f32_16x16x32_bf16 v[98:101], v[146:149], v[232:235], v[98:101]
	v_mfma_f32_16x16x32_bf16 v[90:93], v[160:163], v[232:235], v[90:93]
	v_mfma_f32_16x16x32_bf16 v[82:85], v[146:149], v[240:243], v[82:85]
	v_mfma_f32_16x16x32_bf16 v[74:77], v[160:163], v[240:243], v[74:77]
	s_setprio 0
	s_setprio 1
	v_mfma_f32_16x16x32_bf16 v[118:121], v[164:167], v[180:183], v[118:121]
	v_mfma_f32_16x16x32_bf16 v[110:113], v[172:175], v[180:183], v[110:113]
	v_mfma_f32_16x16x32_bf16 v[102:105], v[164:167], v[196:199], v[102:105]
	v_mfma_f32_16x16x32_bf16 v[94:97], v[172:175], v[196:199], v[94:97]
	v_mfma_f32_16x16x32_bf16 v[86:89], v[164:167], v[228:231], v[86:89]
	v_mfma_f32_16x16x32_bf16 v[78:81], v[172:175], v[228:231], v[78:81]
	v_mfma_f32_16x16x32_bf16 v[70:73], v[164:167], v[236:239], v[70:73]
	v_mfma_f32_16x16x32_bf16 v[66:69], v[172:175], v[236:239], v[66:69]
	v_mfma_f32_16x16x32_bf16 v[118:121], v[168:171], v[184:187], v[118:121]
	v_mfma_f32_16x16x32_bf16 v[110:113], v[176:179], v[184:187], v[110:113]
	v_mfma_f32_16x16x32_bf16 v[102:105], v[168:171], v[200:203], v[102:105]
	v_mfma_f32_16x16x32_bf16 v[94:97], v[176:179], v[200:203], v[94:97]
	v_mfma_f32_16x16x32_bf16 v[86:89], v[168:171], v[232:235], v[86:89]
	v_mfma_f32_16x16x32_bf16 v[78:81], v[176:179], v[232:235], v[78:81]
	v_mfma_f32_16x16x32_bf16 v[70:73], v[168:171], v[240:243], v[70:73]
	v_mfma_f32_16x16x32_bf16 v[66:69], v[176:179], v[240:243], v[66:69]
	s_setprio 0
	s_barrier
	s_add_i32 s64, s19, s10
	v_lshl_add_u64 v[150:151], v[150:151], 0, s[12:13]
	s_mov_b32 m0, s64
	ds_read_b128 v[180:183], v155 offset:49152
	ds_read_b128 v[184:187], v155 offset:50176
	ds_read_b128 v[196:199], v155 offset:51200
	ds_read_b128 v[200:203], v155 offset:52224
	ds_read_b128 v[228:231], v155 offset:53248
	ds_read_b128 v[232:235], v155 offset:54272
	ds_read_b128 v[236:239], v155 offset:55296
	ds_read_b128 v[240:243], v155 offset:56320
	global_load_lds_dwordx4 v[150:151], off
	s_add_i32 m0, s64, 0x2000
	s_add_u32 s62, s62, 0x40080
	v_lshl_add_u64 v[150:151], v[188:189], 0, s[12:13]
	s_addc_u32 s63, s63, 0
	s_add_i32 s64, s72, s10
	global_load_lds_dwordx4 v[150:151], off
	v_lshl_add_u64 v[150:151], s[62:63], 0, v[0:1]
	s_mov_b32 m0, s64
	s_nop 0
	global_load_lds_dwordx4 v[150:151], off
	v_lshl_add_u64 v[150:151], s[62:63], 0, v[130:131]
	s_add_i32 m0, s64, 0x2000
	s_nop 0
	global_load_lds_dwordx4 v[150:151], off
	v_lshl_add_u64 v[150:151], v[190:191], 0, s[12:13]
	s_mov_b32 m0, s39
	s_nop 0
	global_load_lds_dwordx4 v[150:151], off
	v_lshl_add_u64 v[150:151], v[192:193], 0, s[12:13]
	s_mov_b32 m0, s41
	s_nop 0
	global_load_lds_dwordx4 v[150:151], off
	s_waitcnt vmcnt(8)
	s_waitcnt lgkmcnt(0)
	s_barrier
	s_setprio 1
	s_waitcnt lgkmcnt(0)
	v_mfma_f32_16x16x32_bf16 v[62:65], v[142:145], v[180:183], v[62:65]
	v_mfma_f32_16x16x32_bf16 v[58:61], v[156:159], v[180:183], v[58:61]
	v_mfma_f32_16x16x32_bf16 v[50:53], v[142:145], v[196:199], v[50:53]
	v_mfma_f32_16x16x32_bf16 v[42:45], v[156:159], v[196:199], v[42:45]
	v_mfma_f32_16x16x32_bf16 v[34:37], v[142:145], v[228:231], v[34:37]
	v_mfma_f32_16x16x32_bf16 v[26:29], v[156:159], v[228:231], v[26:29]
	v_mfma_f32_16x16x32_bf16 v[18:21], v[142:145], v[236:239], v[18:21]
	v_mfma_f32_16x16x32_bf16 v[10:13], v[156:159], v[236:239], v[10:13]
	v_mfma_f32_16x16x32_bf16 v[62:65], v[146:149], v[184:187], v[62:65]
	v_mfma_f32_16x16x32_bf16 v[58:61], v[160:163], v[184:187], v[58:61]
	v_mfma_f32_16x16x32_bf16 v[50:53], v[146:149], v[200:203], v[50:53]
	v_mfma_f32_16x16x32_bf16 v[42:45], v[160:163], v[200:203], v[42:45]
	v_mfma_f32_16x16x32_bf16 v[34:37], v[146:149], v[232:235], v[34:37]
	v_mfma_f32_16x16x32_bf16 v[26:29], v[160:163], v[232:235], v[26:29]
	v_mfma_f32_16x16x32_bf16 v[18:21], v[146:149], v[240:243], v[18:21]
	v_mfma_f32_16x16x32_bf16 v[10:13], v[160:163], v[240:243], v[10:13]
	s_setprio 0
	s_setprio 1
	v_mfma_f32_16x16x32_bf16 v[54:57], v[164:167], v[180:183], v[54:57]
	v_mfma_f32_16x16x32_bf16 v[46:49], v[172:175], v[180:183], v[46:49]
	v_mfma_f32_16x16x32_bf16 v[38:41], v[164:167], v[196:199], v[38:41]
	v_mfma_f32_16x16x32_bf16 v[30:33], v[172:175], v[196:199], v[30:33]
	v_mfma_f32_16x16x32_bf16 v[22:25], v[164:167], v[228:231], v[22:25]
	v_mfma_f32_16x16x32_bf16 v[14:17], v[172:175], v[228:231], v[14:17]
	v_mfma_f32_16x16x32_bf16 v[6:9], v[164:167], v[236:239], v[6:9]
	v_mfma_f32_16x16x32_bf16 v[2:5], v[172:175], v[236:239], v[2:5]
	v_mfma_f32_16x16x32_bf16 v[54:57], v[168:171], v[184:187], v[54:57]
	v_mfma_f32_16x16x32_bf16 v[46:49], v[176:179], v[184:187], v[46:49]
	v_mfma_f32_16x16x32_bf16 v[38:41], v[168:171], v[200:203], v[38:41]
	v_mfma_f32_16x16x32_bf16 v[30:33], v[176:179], v[200:203], v[30:33]
	v_mfma_f32_16x16x32_bf16 v[22:25], v[168:171], v[232:235], v[22:25]
	v_mfma_f32_16x16x32_bf16 v[14:17], v[176:179], v[232:235], v[14:17]
	v_mfma_f32_16x16x32_bf16 v[6:9], v[168:171], v[240:243], v[6:9]
	v_mfma_f32_16x16x32_bf16 v[2:5], v[176:179], v[240:243], v[2:5]
	s_setprio 0
	s_barrier
	s_add_i32 s71, s71, 2
	s_add_u32 s60, s60, 0x100
	s_addc_u32 s61, s61, 0
	s_add_u32 s69, s69, 0x100
	s_addc_u32 s70, s70, 0
	s_cmp_gt_u32 s71, 13
	s_cbranch_scc0 .LBB0_468
	v_lshl_add_u32 v144, s44, 8, v152
	v_ashrrev_i32_e32 v145, 31, v144
	v_or_b32_e32 v150, 16, v144
	v_or_b32_e32 v148, 32, v144
	v_or_b32_e32 v146, 48, v144
	s_and_b64 vcc, exec, s[50:51]
	s_cbranch_vccz .Lel_no_1
	v_ashrrev_i32_e32 v151, 31, v150
	v_lshlrev_b64 v[142:143], 6, v[144:145]
	v_lshlrev_b64 v[156:157], 6, v[150:151]
	v_lshl_add_u64 v[142:143], v[136:137], 0, v[142:143]
	v_lshl_add_u64 v[160:161], v[136:137], 0, v[156:157]
	v_ashrrev_i32_e32 v149, 31, v148
	v_ashrrev_i32_e32 v147, 31, v146
	global_load_dwordx4 v[156:159], v[142:143], off
	s_nop 0
	global_load_dwordx4 v[160:163], v[160:161], off
	v_lshlrev_b64 v[142:143], 6, v[148:149]
	v_lshlrev_b64 v[164:165], 6, v[146:147]
	v_lshl_add_u64 v[142:143], v[136:137], 0, v[142:143]
	v_lshl_add_u64 v[168:169], v[136:137], 0, v[164:165]
	global_load_dwordx4 v[164:167], v[142:143], off
	s_nop 0
	global_load_dwordx4 v[168:171], v[168:169], off
	v_add_u32_e32 v192, 0x80, v144
	v_ashrrev_i32_e32 v193, 31, v192
	v_lshlrev_b64 v[192:193], 6, v[192:193]
	v_lshl_add_u64 v[192:193], v[136:137], 0, v[192:193]
	global_load_dwordx4 v[176:179], v[192:193], off
	global_load_dwordx4 v[180:183], v[192:193], off offset:1024
	global_load_dwordx4 v[184:187], v[192:193], off offset:2048
	global_load_dwordx4 v[188:191], v[192:193], off offset:3072
.Lel_no_1:
	s_and_b64 vcc, exec, s[48:49]
	s_cbranch_vccz .LBB0_471
	s_barrier
.LBB0_471:
	s_and_b64 vcc, exec, s[50:51]
	s_mov_b32 s53, 0x800000
	s_cbranch_vccz .LBB0_480
	v_cmp_lt_i32_e32 vcc, v218, v213
	s_waitcnt vmcnt(0)
	v_mov_b32_e32 v143, v160
	v_mov_b32_e32 v160, v157
	v_cndmask_b32_e32 v142, v211, v218, vcc
	v_cmp_lt_i32_e32 vcc, v219, v213
	v_lshlrev_b32_e32 v145, 2, v142
	v_mov_b32_e32 v157, v162
	v_cndmask_b32_e32 v142, v211, v219, vcc
	v_lshlrev_b32_e32 v172, 2, v142
	v_mov_b32_e32 v142, v156
	v_mov_b32_e32 v156, v158
	v_mov_b32_e32 v162, v159
	v_pk_add_f32 v[142:143], v[142:143], v[160:161]
	v_pk_add_f32 v[156:157], v[156:157], v[162:163]
	v_add_f32_e32 v160, v164, v165
	v_pk_add_f32 v[142:143], v[142:143], v[156:157]
	ds_bpermute_b32 v156, v145, v142
	ds_bpermute_b32 v157, v145, v143
	v_mov_b32_e32 v164, v169
	v_mov_b32_e32 v165, v170
	v_mov_b32_e32 v169, v171
	v_pk_add_f32 v[164:165], v[164:165], v[168:169]
	s_waitcnt lgkmcnt(0)
	v_pk_add_f32 v[142:143], v[142:143], v[156:157]
	ds_bpermute_b32 v156, v172, v142
	ds_bpermute_b32 v157, v172, v143
	v_add_f32_e32 v162, v166, v167
	v_mov_b32_e32 v161, v164
	v_mov_b32_e32 v163, v165
	v_pk_add_f32 v[160:161], v[160:161], v[162:163]
	ds_bpermute_b32 v162, v145, v160
	ds_bpermute_b32 v163, v145, v161
	s_mov_b32 s44, 0x358637bd
	s_waitcnt lgkmcnt(2)
	v_pk_add_f32 v[142:143], v[142:143], v[156:157]
	v_mov_b64_e32 v[158:159], s[44:45]
	s_mov_b32 s62, 0x3a800000
	v_pk_fma_f32 v[142:143], v[142:143], s[62:63], v[158:159] op_sel_hi:[1,0,0]
	s_waitcnt lgkmcnt(0)
	v_pk_add_f32 v[160:161], v[160:161], v[162:163]
	v_mul_f32_e32 v156, 0x4b800000, v142
	v_cmp_gt_f32_e64 s[44:45], s53, v142
	v_cmp_gt_f32_e32 vcc, s53, v143
	ds_bpermute_b32 v162, v172, v160
	v_cndmask_b32_e64 v142, v142, v156, s[44:45]
	v_mul_f32_e32 v156, 0x4b800000, v143
	ds_bpermute_b32 v163, v172, v161
	v_cndmask_b32_e32 v143, v143, v156, vcc
	v_rsq_f32_e32 v142, v142
	v_rsq_f32_e32 v143, v143
	s_mov_b32 s60, 0x45800000
	s_waitcnt lgkmcnt(0)
	v_pk_add_f32 v[160:161], v[160:161], v[162:163]
	v_pk_mul_f32 v[156:157], v[142:143], s[60:61] op_sel_hi:[1,0]
	v_pk_fma_f32 v[158:159], v[160:161], s[62:63], v[158:159] op_sel_hi:[1,0,0]
	v_cndmask_b32_e64 v142, v142, v156, s[44:45]
	v_cndmask_b32_e32 v156, v143, v157, vcc
	v_mul_f32_e32 v143, 0x4b800000, v158
	v_cmp_gt_f32_e64 s[44:45], s53, v158
	v_cmp_gt_f32_e32 vcc, s53, v159
	s_nop 0
	v_cndmask_b32_e64 v143, v158, v143, s[44:45]
	v_rsq_f32_e32 v158, v143
	v_mul_f32_e32 v143, 0x4b800000, v159
	v_cndmask_b32_e32 v143, v159, v143, vcc
	v_rsq_f32_e32 v159, v143
	s_nop 0
	v_pk_mul_f32 v[160:161], v[158:159], s[60:61] op_sel_hi:[1,0]
	s_nop 0
	v_cndmask_b32_e64 v158, v158, v160, s[44:45]
	v_cndmask_b32_e32 v157, v159, v161, vcc
	v_mov_b32_e32 v238, v195
	s_cbranch_execnz .LBB0_474

.LBB0_654:
	s_add_u32 s54, s44, 0xfffc0080
	s_addc_u32 s55, s45, -1
	s_add_i32 s63, 0, 0x10000
	s_cmp_eq_u32 s62, 12
	s_cselect_b32 s57, s49, s55
	s_cselect_b32 s56, s58, s54
	v_add_u32_e32 v150, s63, v155
	s_cselect_b32 s55, s41, s61
	s_cselect_b32 s54, s59, s60
	s_add_i32 s66, 0, 0x14000
	ds_read_b128 v[142:145], v150
	ds_read_b128 v[146:149], v150 offset:1024
	ds_read_b128 v[160:163], v150 offset:2048
	ds_read_b128 v[164:167], v150 offset:3072
	v_add_u32_e32 v150, s66, v155
	ds_read_b128 v[168:171], v150
	ds_read_b128 v[172:175], v150 offset:1024
	ds_read_b128 v[176:179], v150 offset:2048
	ds_read_b128 v[180:183], v150 offset:3072
	v_lshl_add_u64 v[150:151], s[44:45], 0, v[138:139]
	s_add_i32 m0, s9, 0xc000
	ds_read_b128 v[184:187], v159
	ds_read_b128 v[188:191], v159 offset:1024
	ds_read_b128 v[196:199], v159 offset:2048
	ds_read_b128 v[200:203], v159 offset:3072
	ds_read_b128 v[204:207], v159 offset:4096
	ds_read_b128 v[214:217], v159 offset:5120
	ds_read_b128 v[228:231], v159 offset:6144
	ds_read_b128 v[232:235], v159 offset:7168
	global_load_lds_dwordx4 v[150:151], off
	v_lshl_add_u64 v[150:151], s[44:45], 0, v[140:141]
	s_add_i32 m0, s9, 0xe000
	s_nop 0
	global_load_lds_dwordx4 v[150:151], off
	s_waitcnt vmcnt(8)
	s_waitcnt lgkmcnt(0)
	s_barrier
	s_setprio 1
	s_waitcnt lgkmcnt(0)
	v_mfma_f32_16x16x32_bf16 v[126:129], v[142:145], v[184:187], v[126:129]
	v_mfma_f32_16x16x32_bf16 v[122:125], v[160:163], v[184:187], v[122:125]
	v_mfma_f32_16x16x32_bf16 v[110:113], v[142:145], v[196:199], v[110:113]
	v_mfma_f32_16x16x32_bf16 v[106:109], v[160:163], v[196:199], v[106:109]
	v_mfma_f32_16x16x32_bf16 v[94:97], v[142:145], v[204:207], v[94:97]
	v_mfma_f32_16x16x32_bf16 v[90:93], v[160:163], v[204:207], v[90:93]
	v_mfma_f32_16x16x32_bf16 v[78:81], v[142:145], v[228:231], v[78:81]
	v_mfma_f32_16x16x32_bf16 v[74:77], v[160:163], v[228:231], v[74:77]
	v_mfma_f32_16x16x32_bf16 v[126:129], v[146:149], v[188:191], v[126:129]
	v_mfma_f32_16x16x32_bf16 v[122:125], v[164:167], v[188:191], v[122:125]
	v_mfma_f32_16x16x32_bf16 v[110:113], v[146:149], v[200:203], v[110:113]
	v_mfma_f32_16x16x32_bf16 v[106:109], v[164:167], v[200:203], v[106:109]
	v_mfma_f32_16x16x32_bf16 v[94:97], v[146:149], v[214:217], v[94:97]
	v_mfma_f32_16x16x32_bf16 v[90:93], v[164:167], v[214:217], v[90:93]
	v_mfma_f32_16x16x32_bf16 v[78:81], v[146:149], v[232:235], v[78:81]
	v_mfma_f32_16x16x32_bf16 v[74:77], v[164:167], v[232:235], v[74:77]
	s_setprio 0
	s_setprio 1
	v_mfma_f32_16x16x32_bf16 v[118:121], v[168:171], v[184:187], v[118:121]
	v_mfma_f32_16x16x32_bf16 v[114:117], v[176:179], v[184:187], v[114:117]
	v_mfma_f32_16x16x32_bf16 v[102:105], v[168:171], v[196:199], v[102:105]
	v_mfma_f32_16x16x32_bf16 v[98:101], v[176:179], v[196:199], v[98:101]
	v_mfma_f32_16x16x32_bf16 v[86:89], v[168:171], v[204:207], v[86:89]
	v_mfma_f32_16x16x32_bf16 v[82:85], v[176:179], v[204:207], v[82:85]
	v_mfma_f32_16x16x32_bf16 v[70:73], v[168:171], v[228:231], v[70:73]
	v_mfma_f32_16x16x32_bf16 v[66:69], v[176:179], v[228:231], v[66:69]
	v_mfma_f32_16x16x32_bf16 v[118:121], v[172:175], v[188:191], v[118:121]
	v_mfma_f32_16x16x32_bf16 v[114:117], v[180:183], v[188:191], v[114:117]
	v_mfma_f32_16x16x32_bf16 v[102:105], v[172:175], v[200:203], v[102:105]
	v_mfma_f32_16x16x32_bf16 v[98:101], v[180:183], v[200:203], v[98:101]
	v_mfma_f32_16x16x32_bf16 v[86:89], v[172:175], v[214:217], v[86:89]
	v_mfma_f32_16x16x32_bf16 v[82:85], v[180:183], v[214:217], v[82:85]
	v_mfma_f32_16x16x32_bf16 v[70:73], v[172:175], v[232:235], v[70:73]
	v_mfma_f32_16x16x32_bf16 v[66:69], v[180:183], v[232:235], v[66:69]
	s_setprio 0
	s_barrier
	s_add_i32 s63, s63, s5
	v_lshl_add_u64 v[150:151], s[54:55], 0, v[0:1]
	s_mov_b32 m0, s63
	ds_read_b128 v[184:187], v159 offset:16384
	ds_read_b128 v[188:191], v159 offset:17408
	ds_read_b128 v[196:199], v159 offset:18432
	ds_read_b128 v[200:203], v159 offset:19456
	ds_read_b128 v[204:207], v159 offset:20480
	ds_read_b128 v[214:217], v159 offset:21504
	ds_read_b128 v[228:231], v159 offset:22528
	ds_read_b128 v[232:235], v159 offset:23552
	global_load_lds_dwordx4 v[150:151], off
	s_add_i32 m0, s63, 0x2000
	s_add_u32 s64, s54, 0x40000
	v_lshl_add_u64 v[192:193], s[54:55], 0, v[130:131]
	s_addc_u32 s65, s55, 0
	s_add_i32 s63, s66, s5
	global_load_lds_dwordx4 v[192:193], off
	v_lshl_add_u64 v[208:209], s[64:65], 0, v[0:1]
	s_mov_b32 m0, s63
	v_lshl_add_u64 v[236:237], s[56:57], 0, v[132:133]
	global_load_lds_dwordx4 v[208:209], off
	v_lshl_add_u64 v[208:209], s[64:65], 0, v[130:131]
	s_add_i32 m0, s63, 0x2000
	s_nop 0
	global_load_lds_dwordx4 v[208:209], off
	v_lshl_add_u64 v[208:209], s[56:57], 0, v[134:135]
	s_mov_b32 m0, s9
	s_nop 0
	global_load_lds_dwordx4 v[208:209], off
	s_mov_b32 m0, s10
	s_nop 0
	global_load_lds_dwordx4 v[236:237], off
	s_waitcnt vmcnt(8)
	s_waitcnt lgkmcnt(0)
	s_barrier
	s_setprio 1
	s_waitcnt lgkmcnt(0)
	v_mfma_f32_16x16x32_bf16 v[62:65], v[142:145], v[184:187], v[62:65]
	v_mfma_f32_16x16x32_bf16 v[58:61], v[160:163], v[184:187], v[58:61]
	v_mfma_f32_16x16x32_bf16 v[46:49], v[142:145], v[196:199], v[46:49]
	v_mfma_f32_16x16x32_bf16 v[42:45], v[160:163], v[196:199], v[42:45]
	v_mfma_f32_16x16x32_bf16 v[30:33], v[142:145], v[204:207], v[30:33]
	v_mfma_f32_16x16x32_bf16 v[26:29], v[160:163], v[204:207], v[26:29]
	v_mfma_f32_16x16x32_bf16 v[14:17], v[142:145], v[228:231], v[14:17]
	v_mfma_f32_16x16x32_bf16 v[10:13], v[160:163], v[228:231], v[10:13]
	v_mfma_f32_16x16x32_bf16 v[62:65], v[146:149], v[188:191], v[62:65]
	v_mfma_f32_16x16x32_bf16 v[58:61], v[164:167], v[188:191], v[58:61]
	v_mfma_f32_16x16x32_bf16 v[46:49], v[146:149], v[200:203], v[46:49]
	v_mfma_f32_16x16x32_bf16 v[42:45], v[164:167], v[200:203], v[42:45]
	v_mfma_f32_16x16x32_bf16 v[30:33], v[146:149], v[214:217], v[30:33]
	v_mfma_f32_16x16x32_bf16 v[26:29], v[164:167], v[214:217], v[26:29]
	v_mfma_f32_16x16x32_bf16 v[14:17], v[146:149], v[232:235], v[14:17]
	v_mfma_f32_16x16x32_bf16 v[10:13], v[164:167], v[232:235], v[10:13]
	s_setprio 0
	s_setprio 1
	v_mfma_f32_16x16x32_bf16 v[54:57], v[168:171], v[184:187], v[54:57]
	v_mfma_f32_16x16x32_bf16 v[50:53], v[176:179], v[184:187], v[50:53]
	v_mfma_f32_16x16x32_bf16 v[38:41], v[168:171], v[196:199], v[38:41]
	v_mfma_f32_16x16x32_bf16 v[34:37], v[176:179], v[196:199], v[34:37]
	v_mfma_f32_16x16x32_bf16 v[22:25], v[168:171], v[204:207], v[22:25]
	v_mfma_f32_16x16x32_bf16 v[18:21], v[176:179], v[204:207], v[18:21]
	v_mfma_f32_16x16x32_bf16 v[6:9], v[168:171], v[228:231], v[6:9]
	v_mfma_f32_16x16x32_bf16 v[2:5], v[176:179], v[228:231], v[2:5]
	v_mfma_f32_16x16x32_bf16 v[54:57], v[172:175], v[188:191], v[54:57]
	v_mfma_f32_16x16x32_bf16 v[50:53], v[180:183], v[188:191], v[50:53]
	v_mfma_f32_16x16x32_bf16 v[38:41], v[172:175], v[200:203], v[38:41]
	v_mfma_f32_16x16x32_bf16 v[34:37], v[180:183], v[200:203], v[34:37]
	v_mfma_f32_16x16x32_bf16 v[22:25], v[172:175], v[214:217], v[22:25]
	v_mfma_f32_16x16x32_bf16 v[18:21], v[180:183], v[214:217], v[18:21]
	v_mfma_f32_16x16x32_bf16 v[6:9], v[172:175], v[232:235], v[6:9]
	v_mfma_f32_16x16x32_bf16 v[2:5], v[180:183], v[232:235], v[2:5]
	s_setprio 0
	s_barrier
	v_add_u32_e32 v152, s19, v155
	s_add_i32 s63, 0, 0x1c000
	ds_read_b128 v[142:145], v152
	ds_read_b128 v[146:149], v152 offset:1024
	ds_read_b128 v[160:163], v152 offset:2048
	ds_read_b128 v[164:167], v152 offset:3072
	v_add_u32_e32 v152, s63, v155
	ds_read_b128 v[168:171], v152
	ds_read_b128 v[172:175], v152 offset:1024
	ds_read_b128 v[176:179], v152 offset:2048
	ds_read_b128 v[180:183], v152 offset:3072
	s_add_u32 s56, s56, 0x40000
	s_addc_u32 s57, s57, 0
	s_mov_b32 m0, s11
	v_lshl_add_u64 v[238:239], s[56:57], 0, v[134:135]
	ds_read_b128 v[184:187], v159 offset:32768
	ds_read_b128 v[188:191], v159 offset:33792
	ds_read_b128 v[196:199], v159 offset:34816
	ds_read_b128 v[200:203], v159 offset:35840
	ds_read_b128 v[204:207], v159 offset:36864
	ds_read_b128 v[214:217], v159 offset:37888
	ds_read_b128 v[228:231], v159 offset:38912
	ds_read_b128 v[232:235], v159 offset:39936
	global_load_lds_dwordx4 v[238:239], off
	v_lshl_add_u64 v[238:239], s[56:57], 0, v[132:133]
	s_mov_b32 m0, s22
	s_nop 0
	global_load_lds_dwordx4 v[238:239], off
	s_waitcnt vmcnt(8)
	s_waitcnt lgkmcnt(0)
	s_barrier
	s_setprio 1
	s_waitcnt lgkmcnt(0)
	v_mfma_f32_16x16x32_bf16 v[126:129], v[142:145], v[184:187], v[126:129]
	v_mfma_f32_16x16x32_bf16 v[122:125], v[160:163], v[184:187], v[122:125]
	v_mfma_f32_16x16x32_bf16 v[110:113], v[142:145], v[196:199], v[110:113]
	v_mfma_f32_16x16x32_bf16 v[106:109], v[160:163], v[196:199], v[106:109]
	v_mfma_f32_16x16x32_bf16 v[94:97], v[142:145], v[204:207], v[94:97]
	v_mfma_f32_16x16x32_bf16 v[90:93], v[160:163], v[204:207], v[90:93]
	v_mfma_f32_16x16x32_bf16 v[78:81], v[142:145], v[228:231], v[78:81]
	v_mfma_f32_16x16x32_bf16 v[74:77], v[160:163], v[228:231], v[74:77]
	v_mfma_f32_16x16x32_bf16 v[126:129], v[146:149], v[188:191], v[126:129]
	v_mfma_f32_16x16x32_bf16 v[122:125], v[164:167], v[188:191], v[122:125]
	v_mfma_f32_16x16x32_bf16 v[110:113], v[146:149], v[200:203], v[110:113]
	v_mfma_f32_16x16x32_bf16 v[106:109], v[164:167], v[200:203], v[106:109]
	v_mfma_f32_16x16x32_bf16 v[94:97], v[146:149], v[214:217], v[94:97]
	v_mfma_f32_16x16x32_bf16 v[90:93], v[164:167], v[214:217], v[90:93]
	v_mfma_f32_16x16x32_bf16 v[78:81], v[146:149], v[232:235], v[78:81]
	v_mfma_f32_16x16x32_bf16 v[74:77], v[164:167], v[232:235], v[74:77]
	s_setprio 0
	s_setprio 1
	v_mfma_f32_16x16x32_bf16 v[118:121], v[168:171], v[184:187], v[118:121]
	v_mfma_f32_16x16x32_bf16 v[114:117], v[176:179], v[184:187], v[114:117]
	v_mfma_f32_16x16x32_bf16 v[102:105], v[168:171], v[196:199], v[102:105]
	v_mfma_f32_16x16x32_bf16 v[98:101], v[176:179], v[196:199], v[98:101]
	v_mfma_f32_16x16x32_bf16 v[86:89], v[168:171], v[204:207], v[86:89]
	v_mfma_f32_16x16x32_bf16 v[82:85], v[176:179], v[204:207], v[82:85]
	v_mfma_f32_16x16x32_bf16 v[70:73], v[168:171], v[228:231], v[70:73]
	v_mfma_f32_16x16x32_bf16 v[66:69], v[176:179], v[228:231], v[66:69]
	v_mfma_f32_16x16x32_bf16 v[118:121], v[172:175], v[188:191], v[118:121]
	v_mfma_f32_16x16x32_bf16 v[114:117], v[180:183], v[188:191], v[114:117]
	v_mfma_f32_16x16x32_bf16 v[102:105], v[172:175], v[200:203], v[102:105]
	v_mfma_f32_16x16x32_bf16 v[98:101], v[180:183], v[200:203], v[98:101]
	v_mfma_f32_16x16x32_bf16 v[86:89], v[172:175], v[214:217], v[86:89]
	v_mfma_f32_16x16x32_bf16 v[82:85], v[180:183], v[214:217], v[82:85]
	v_mfma_f32_16x16x32_bf16 v[70:73], v[172:175], v[232:235], v[70:73]
	v_mfma_f32_16x16x32_bf16 v[66:69], v[180:183], v[232:235], v[66:69]
	s_setprio 0
	s_barrier
	s_add_i32 s56, s19, s5
	v_lshl_add_u64 v[150:151], v[150:151], 0, s[12:13]
	s_mov_b32 m0, s56
	ds_read_b128 v[184:187], v159 offset:49152
	ds_read_b128 v[188:191], v159 offset:50176
	ds_read_b128 v[196:199], v159 offset:51200
	ds_read_b128 v[200:203], v159 offset:52224
	ds_read_b128 v[204:207], v159 offset:53248
	ds_read_b128 v[214:217], v159 offset:54272
	ds_read_b128 v[228:231], v159 offset:55296
	ds_read_b128 v[232:235], v159 offset:56320
	global_load_lds_dwordx4 v[150:151], off
	s_add_i32 m0, s56, 0x2000
	s_add_u32 s54, s54, 0x40080
	v_lshl_add_u64 v[150:151], v[192:193], 0, s[12:13]
	s_addc_u32 s55, s55, 0
	s_add_i32 s56, s63, s5
	global_load_lds_dwordx4 v[150:151], off
	v_lshl_add_u64 v[150:151], s[54:55], 0, v[0:1]
	s_mov_b32 m0, s56
	s_nop 0
	global_load_lds_dwordx4 v[150:151], off
	v_lshl_add_u64 v[150:151], s[54:55], 0, v[130:131]
	s_add_i32 m0, s56, 0x2000
	s_nop 0
	global_load_lds_dwordx4 v[150:151], off
	v_lshl_add_u64 v[150:151], v[208:209], 0, s[12:13]
	s_mov_b32 m0, s23
	s_nop 0
	global_load_lds_dwordx4 v[150:151], off
	v_lshl_add_u64 v[150:151], v[236:237], 0, s[12:13]
	s_mov_b32 m0, s26
	s_nop 0
	global_load_lds_dwordx4 v[150:151], off
	s_waitcnt vmcnt(8)
	s_waitcnt lgkmcnt(0)
	s_barrier
	s_setprio 1
	s_waitcnt lgkmcnt(0)
	v_mfma_f32_16x16x32_bf16 v[62:65], v[142:145], v[184:187], v[62:65]
	v_mfma_f32_16x16x32_bf16 v[58:61], v[160:163], v[184:187], v[58:61]
	v_mfma_f32_16x16x32_bf16 v[46:49], v[142:145], v[196:199], v[46:49]
	v_mfma_f32_16x16x32_bf16 v[42:45], v[160:163], v[196:199], v[42:45]
	v_mfma_f32_16x16x32_bf16 v[30:33], v[142:145], v[204:207], v[30:33]
	v_mfma_f32_16x16x32_bf16 v[26:29], v[160:163], v[204:207], v[26:29]
	v_mfma_f32_16x16x32_bf16 v[14:17], v[142:145], v[228:231], v[14:17]
	v_mfma_f32_16x16x32_bf16 v[10:13], v[160:163], v[228:231], v[10:13]
	v_mfma_f32_16x16x32_bf16 v[62:65], v[146:149], v[188:191], v[62:65]
	v_mfma_f32_16x16x32_bf16 v[58:61], v[164:167], v[188:191], v[58:61]
	v_mfma_f32_16x16x32_bf16 v[46:49], v[146:149], v[200:203], v[46:49]
	v_mfma_f32_16x16x32_bf16 v[42:45], v[164:167], v[200:203], v[42:45]
	v_mfma_f32_16x16x32_bf16 v[30:33], v[146:149], v[214:217], v[30:33]
	v_mfma_f32_16x16x32_bf16 v[26:29], v[164:167], v[214:217], v[26:29]
	v_mfma_f32_16x16x32_bf16 v[14:17], v[146:149], v[232:235], v[14:17]
	v_mfma_f32_16x16x32_bf16 v[10:13], v[164:167], v[232:235], v[10:13]
	s_setprio 0
	s_setprio 1
	v_mfma_f32_16x16x32_bf16 v[54:57], v[168:171], v[184:187], v[54:57]
	v_mfma_f32_16x16x32_bf16 v[50:53], v[176:179], v[184:187], v[50:53]
	v_mfma_f32_16x16x32_bf16 v[38:41], v[168:171], v[196:199], v[38:41]
	v_mfma_f32_16x16x32_bf16 v[34:37], v[176:179], v[196:199], v[34:37]
	v_mfma_f32_16x16x32_bf16 v[22:25], v[168:171], v[204:207], v[22:25]
	v_mfma_f32_16x16x32_bf16 v[18:21], v[176:179], v[204:207], v[18:21]
	v_mfma_f32_16x16x32_bf16 v[6:9], v[168:171], v[228:231], v[6:9]
	v_mfma_f32_16x16x32_bf16 v[2:5], v[176:179], v[228:231], v[2:5]
	v_mfma_f32_16x16x32_bf16 v[54:57], v[172:175], v[188:191], v[54:57]
	v_mfma_f32_16x16x32_bf16 v[50:53], v[180:183], v[188:191], v[50:53]
	v_mfma_f32_16x16x32_bf16 v[38:41], v[172:175], v[200:203], v[38:41]
	v_mfma_f32_16x16x32_bf16 v[34:37], v[180:183], v[200:203], v[34:37]
	v_mfma_f32_16x16x32_bf16 v[22:25], v[172:175], v[214:217], v[22:25]
	v_mfma_f32_16x16x32_bf16 v[18:21], v[180:183], v[214:217], v[18:21]
	v_mfma_f32_16x16x32_bf16 v[6:9], v[172:175], v[232:235], v[6:9]
	v_mfma_f32_16x16x32_bf16 v[2:5], v[180:183], v[232:235], v[2:5]
	s_setprio 0
	s_barrier
	s_add_i32 s62, s62, 2
	s_add_u32 s44, s44, 0x100
	s_addc_u32 s45, s45, 0
	s_add_u32 s60, s60, 0x100
	s_addc_u32 s61, s61, 0
	s_cmp_gt_u32 s62, 13
	s_cbranch_scc0 .LBB0_654
	v_lshl_add_u32 v144, s39, 8, v153
	v_ashrrev_i32_e32 v145, 31, v144
	v_or_b32_e32 v150, 16, v144
	v_or_b32_e32 v148, 32, v144
	v_or_b32_e32 v146, 48, v144
	s_and_b64 vcc, exec, s[46:47]
	s_cbranch_vccz .Lel_no_0
	v_ashrrev_i32_e32 v151, 31, v150
	v_lshlrev_b64 v[142:143], 6, v[144:145]
	v_lshlrev_b64 v[160:161], 6, v[150:151]
	v_lshl_add_u64 v[142:143], v[136:137], 0, v[142:143]
	v_lshl_add_u64 v[164:165], v[136:137], 0, v[160:161]
	v_ashrrev_i32_e32 v149, 31, v148
	v_ashrrev_i32_e32 v147, 31, v146
	global_load_dwordx4 v[160:163], v[142:143], off
	s_nop 0
	global_load_dwordx4 v[164:167], v[164:165], off
	v_lshlrev_b64 v[142:143], 6, v[148:149]
	v_lshlrev_b64 v[168:169], 6, v[146:147]
	v_lshl_add_u64 v[142:143], v[136:137], 0, v[142:143]
	v_lshl_add_u64 v[172:173], v[136:137], 0, v[168:169]
	global_load_dwordx4 v[168:171], v[142:143], off
	s_nop 0
	global_load_dwordx4 v[172:175], v[172:173], off
	v_add_u32_e32 v192, 0x80, v144
	v_ashrrev_i32_e32 v193, 31, v192
	v_lshlrev_b64 v[192:193], 6, v[192:193]
	v_lshl_add_u64 v[192:193], v[136:137], 0, v[192:193]
	global_load_dwordx4 v[176:179], v[192:193], off
	global_load_dwordx4 v[180:183], v[192:193], off offset:1024
	global_load_dwordx4 v[184:187], v[192:193], off offset:2048
	global_load_dwordx4 v[188:191], v[192:193], off offset:3072
.Lel_no_0:
	s_and_b64 vcc, exec, s[30:31]
	s_cbranch_vccz .LBB0_657
	s_barrier
.LBB0_657:
	s_and_b64 vcc, exec, s[46:47]
	s_mov_b32 s39, 0x800000
	s_cbranch_vccz .LBB0_666
	v_cmp_lt_i32_e32 vcc, v218, v213
	s_waitcnt vmcnt(0)
	v_mov_b32_e32 v143, v164
	v_mov_b32_e32 v164, v161
	v_cndmask_b32_e32 v142, v211, v218, vcc
	v_cmp_lt_i32_e32 vcc, v219, v213
	v_lshlrev_b32_e32 v152, 2, v142
	v_mov_b32_e32 v161, v166
	v_cndmask_b32_e32 v142, v211, v219, vcc
	v_lshlrev_b32_e32 v156, 2, v142
	v_mov_b32_e32 v142, v160
	v_mov_b32_e32 v160, v162
	v_mov_b32_e32 v166, v163
	v_pk_add_f32 v[142:143], v[142:143], v[164:165]
	v_pk_add_f32 v[160:161], v[160:161], v[166:167]
	s_mov_b32 s44, 0x358637bd
	v_pk_add_f32 v[142:143], v[142:143], v[160:161]
	ds_bpermute_b32 v160, v152, v142
	ds_bpermute_b32 v161, v152, v143
	s_mov_b32 s56, 0x3a800000
	s_mov_b32 s54, 0x45800000
	v_mov_b32_e32 v164, v173
	v_mov_b32_e32 v165, v174
	s_waitcnt lgkmcnt(0)
	v_pk_add_f32 v[142:143], v[142:143], v[160:161]
	ds_bpermute_b32 v160, v156, v142
	ds_bpermute_b32 v161, v156, v143
	v_mov_b32_e32 v173, v175
	v_pk_add_f32 v[164:165], v[164:165], v[172:173]
	s_waitcnt lgkmcnt(0)
	v_pk_add_f32 v[142:143], v[142:143], v[160:161]
	v_mov_b64_e32 v[160:161], s[44:45]
	v_pk_fma_f32 v[142:143], v[142:143], s[56:57], v[160:161] op_sel_hi:[1,0,0]
	s_nop 0
	v_mul_f32_e32 v154, 0x4b800000, v142
	v_cmp_gt_f32_e64 s[44:45], s39, v142
	v_cmp_gt_f32_e32 vcc, s39, v143
	s_nop 0
	v_cndmask_b32_e64 v142, v142, v154, s[44:45]
	v_mul_f32_e32 v154, 0x4b800000, v143
	v_cndmask_b32_e32 v143, v143, v154, vcc
	v_rsq_f32_e32 v142, v142
	v_rsq_f32_e32 v143, v143
	s_nop 0
	v_pk_mul_f32 v[162:163], v[142:143], s[54:55] op_sel_hi:[1,0]
	s_nop 0
	v_cndmask_b32_e64 v158, v142, v162, s[44:45]
	v_cndmask_b32_e32 v154, v143, v163, vcc
	v_add_f32_e32 v142, v168, v169
	v_add_f32_e32 v162, v170, v171
	v_mov_b32_e32 v143, v164
	v_mov_b32_e32 v163, v165
	v_pk_add_f32 v[142:143], v[142:143], v[162:163]
	ds_bpermute_b32 v162, v152, v142
	ds_bpermute_b32 v163, v152, v143
	s_waitcnt lgkmcnt(0)
	v_pk_add_f32 v[142:143], v[142:143], v[162:163]
	ds_bpermute_b32 v162, v156, v142
	ds_bpermute_b32 v163, v156, v143
	s_waitcnt lgkmcnt(0)
	v_pk_add_f32 v[142:143], v[142:143], v[162:163]
	s_nop 0
	v_pk_fma_f32 v[142:143], v[142:143], s[56:57], v[160:161] op_sel_hi:[1,0,0]
	s_nop 0
	v_mul_f32_e32 v152, 0x4b800000, v142
	v_cmp_gt_f32_e64 s[44:45], s39, v142
	v_cmp_gt_f32_e32 vcc, s39, v143
	s_nop 0
	v_cndmask_b32_e64 v142, v142, v152, s[44:45]
	v_mul_f32_e32 v152, 0x4b800000, v143
	v_cndmask_b32_e32 v143, v143, v152, vcc
	v_rsq_f32_e32 v142, v142
	v_rsq_f32_e32 v143, v143
	s_nop 0
	v_pk_mul_f32 v[160:161], v[142:143], s[54:55] op_sel_hi:[1,0]
	s_nop 0
	v_cndmask_b32_e64 v156, v142, v160, s[44:45]
	v_cndmask_b32_e32 v152, v143, v161, vcc
	v_mov_b32_e32 v238, v195
	s_cbranch_execnz .LBB0_660
